# mLSTM chunk loop: numerator-stage LDS reads issued together (now that the stage runs straight after QC^T without a barrier)
# speedup vs baseline: 1.1550x; 1.0055x over previous
; __device__ __forceinline__ void mlstm_task(const Ctx& c, int p, int l, int q, int h, int slab) {
;     ...
;         f32x4 num = {0.f, 0.f, 0.f, 0.f};
;         num = mma_tile(St + 16 * ti * 72, 72, VT + 16 * vj * 72, 72, 64, num, lane);
; #pragma unroll
;         for (int r = 0; r < 4; ++r) { const int t = 16 * ti + (lane >> 4) * 4 + r; num[r] = qc[r] * wint[t] + esc[t] * num[r]; }
;         if (w < 4) {
;             f32x4 sv2 = {0.f, 0.f, 0.f, 0.f};
;             sv2 = mma_tile(St + 16 * w * 72, 72, VT + 32 * 72, 72, 64, sv2, lane);
; #pragma unroll
;             for (int r = 0; r < 4; ++r) { const int t = 16 * w + (lane >> 4) * 4 + r; qc2[r] = qc2[r] * wint[t] + esc[t] * sv2[r]; }
;             if ((lane & 15) == 0) {
; #pragma unroll
;                 for (int r = 0; r < 4; ++r) { const int t = 16 * w + (lane >> 4) * 4 + r; dd[t] = fmaxf(fabsf(qc2[r]), __expf(-mts[t])); }
;             }
.LBB0_1631:
	s_nop 2
	ds_read_b128 v[4:7], v122
	ds_read_b128 v[84:87], v123
	ds_read_b128 v[200:203], v122 offset:64
	ds_read_b128 v[204:207], v123 offset:64
	ds_read2_b32 v[110:111], v147 offset1:1
	ds_read2_b32 v[112:113], v148 offset1:1
	ds_read2_b32 v[106:107], v149 offset1:1
	ds_read2_b32 v[108:109], v150 offset1:1
	s_and_b64 vcc, exec, s[68:69]
	s_waitcnt lgkmcnt(6)
	v_mfma_f32_16x16x32_bf16 v[4:7], v[4:7], v[84:87], 0
	s_waitcnt lgkmcnt(4)
	v_mfma_f32_16x16x32_bf16 v[4:7], v[200:203], v[204:207], v[4:7]
	s_cbranch_vccnz .LBB0_1635
	ds_read_b128 v[84:87], v197
	ds_read_b128 v[200:203], v131
	ds_read_b128 v[204:207], v197 offset:64
	ds_read_b128 v[136:139], v131 offset:64
	s_waitcnt lgkmcnt(2)
	v_mfma_f32_16x16x32_bf16 v[84:87], v[84:87], v[200:203], 0
	s_waitcnt lgkmcnt(0)
	v_mfma_f32_16x16x32_bf16 v[84:87], v[204:207], v[136:139], v[84:87]
	s_and_saveexec_b64 s[68:69], s[30:31]
	s_cbranch_execz .LBB0_1634
	ds_read2_b32 v[136:137], v153 offset1:1
	ds_read2_b32 v[138:139], v154 offset1:1
	ds_read2_b32 v[200:201], v151 offset1:1
	ds_read2_b32 v[202:203], v152 offset1:1
	ds_read2_b32 v[204:205], v155 offset1:1
	ds_read2_b32 v[206:207], v157 offset1:1
	s_waitcnt lgkmcnt(4)
	v_mul_f32_e32 v13, v87, v139
	v_fmac_f32_e32 v13, v11, v137
	s_waitcnt lgkmcnt(2)
	v_mul_f32_e32 v11, v84, v202
	v_mul_f32_e32 v84, v85, v203
	v_fmac_f32_e32 v11, v8, v200
	v_fmac_f32_e32 v84, v9, v201
	v_mul_f32_e32 v85, v86, v138
	v_fmac_f32_e32 v85, v10, v136
	s_waitcnt lgkmcnt(0)
	v_mul_f32_e32 v8, 0xbfb8aa3b, v204
	v_mul_f32_e32 v9, 0xbfb8aa3b, v205
	v_exp_f32_e32 v8, v8
	v_exp_f32_e32 v9, v9
	v_mul_f32_e32 v10, 0xbfb8aa3b, v206
	v_mul_f32_e32 v200, 0xbfb8aa3b, v207
	v_exp_f32_e32 v10, v10
	v_exp_f32_e32 v200, v200
	v_max_f32_e64 v8, |v11|, v8
	v_max_f32_e64 v9, |v84|, v9
	ds_write2_b32 v156, v8, v9 offset1:1
	v_max_f32_e64 v10, |v85|, v10
	v_max_f32_e64 v200, |v13|, v200
	ds_write2_b32 v158, v10, v200 offset1:1
